# v93 with the rope cos/sin tables requested two row groups ahead (third register set from dead VGPRs, counted vmcnt 8/9/10/10/10/10/6/2)
# baseline (speedup 1.0000x reference)
; __device__ __forceinline__ u32x4 pack8(const float (&v)[8]) { u32x4 w; w.x = pk2(v[0], v[1]); w.y = pk2(v[2], v[3]); w.z = pk2(v[4], v[5]); w.w = pk2(v[6], v[7]); return w; }
;     __device__ __forceinline__ bool operator()(Acc& acc, const Unit& u, int wr, int wc, int fr, int fq, const LAS float* rstab) const {
;     ...
;                 if (rope) {
;                     const float sgn = (fq == 0) ? -1.f : 1.f;
; #pragma unroll
;                     for (int ai = 0; ai < 2; ++ai)
; #pragma unroll
;                         for (int m = 0; m < 4; ++m) {
;                             const float rs = rsp[ai * HALF + m * 16] * scale;
;                             const int pos = (rowb + ai * HALF + m * 16) & (SEQ - 1);
;                             const f32x4 c0 = gld<f32x4>(ropec + pos * 8), c1 = gld<f32x4>(ropec + pos * 8 + 4);
;                             const f32x4 s0 = gld<f32x4>(ropes + pos * 8), s1 = gld<f32x4>(ropes + pos * 8 + 4);
;                             float v[8];
; #pragma unroll
;                             for (int e = 0; e < 4; ++e) { v[e] = acc[ai][bj][m][0][e] * rs; v[4 + e] = acc[ai][bj][m][1][e] * rs; }
; #pragma unroll
;                             for (int e = 0; e < 8; ++e) {
;                                 const float p = __shfl_xor(v[e], 16);
;                                 const float cs = e < 4 ? c0[e & 3] : c1[e & 3], sn = e < 4 ? s0[e & 3] : s1[e & 3];
;                                 const float r = v[e] * cs + sgn * p * sn;
;                                 v[e] = (fq < 2) ? r : v[e];
;                             }
;                             gst<u32x4>(p0 + (ai * HALF + m * 16) * pitch, pack8(v));
;                             asm volatile("" ::: "memory");
;                         }
.LBB0_419:
	s_andn2_b64 vcc, exec, s[60:61]
	s_cbranch_vccnz .LBB0_421
	v_and_b32_e32 v132, 64, v198
	v_xor_b32_e32 v0, 16, v198
	v_add_u32_e32 v132, 64, v132
	v_cmp_lt_i32_e32 vcc, v0, v132
	s_lshl_b32 s26, s71, 5
	s_mov_b32 s59, s27
	s_mov_b32 s19, s27
	s_mov_b32 s17, s27
	s_mov_b32 s15, s27
	v_cndmask_b32_e32 v0, v198, v0, vcc
	v_lshlrev_b32_e32 v0, 2, v0
	s_mov_b64 s[100:101], exec
	s_andn2_b64 vcc, s[54:55], s[56:57]
	ds_read_b32 v188, v154
	v_lshlrev_b32_e32 v159, 5, v2
	v_and_b32_e32 v159, 0xf9e0, v159
	global_load_dwordx4 v[164:167], v159, s[20:21] offset:16
	global_load_dwordx4 v[160:163], v159, s[20:21]
	global_load_dwordx4 v[172:175], v159, s[22:23] offset:16
	global_load_dwordx4 v[168:171], v159, s[22:23]
	v_or_b32_e32 v143, 0x200, v159
	global_load_dwordx4 v[180:183], v143, s[20:21] offset:16
	global_load_dwordx4 v[176:179], v143, s[20:21]
	global_load_dwordx4 v[190:193], v143, s[22:23] offset:16
	global_load_dwordx4 v[184:187], v143, s[22:23]
	s_waitcnt lgkmcnt(0)
	v_mul_f32_e32 v188, s9, v188
	v_pk_mul_f32 v[212:213], v[120:121], v[188:189] op_sel_hi:[1,0]
	v_pk_mul_f32 v[214:215], v[122:123], v[188:189] op_sel_hi:[1,0]
	v_pk_mul_f32 v[216:217], v[112:113], v[188:189] op_sel_hi:[1,0]
	v_pk_mul_f32 v[218:219], v[114:115], v[188:189] op_sel_hi:[1,0]
	ds_bpermute_b32 v228, v0, v212
	ds_bpermute_b32 v229, v0, v213
	ds_bpermute_b32 v230, v0, v214
	ds_bpermute_b32 v231, v0, v215
	ds_bpermute_b32 v132, v0, v216
	ds_bpermute_b32 v133, v0, v217
	ds_bpermute_b32 v134, v0, v218
	ds_bpermute_b32 v135, v0, v219
	ds_read_b32 v189, v154 offset:64
	v_or_b32_e32 v143, 0x400, v159
	global_load_dwordx4 v[200:203], v143, s[20:21] offset:16
	global_load_dwordx4 v[194:197], v143, s[20:21]
	global_load_dwordx4 v[220:223], v143, s[22:23] offset:16
	global_load_dwordx4 v[206:209], v143, s[22:23]
	s_waitcnt lgkmcnt(1)
	s_waitcnt vmcnt(8)
	v_pk_mul_f32 v[160:161], v[212:213], v[160:161]
	v_pk_mul_f32 v[162:163], v[214:215], v[162:163]
	v_pk_mul_f32 v[164:165], v[216:217], v[164:165]
	v_pk_mul_f32 v[166:167], v[218:219], v[166:167]
	v_pk_mul_f32 v[168:169], v[228:229], v[168:169]
	v_pk_mul_f32 v[170:171], v[230:231], v[170:171]
	v_pk_mul_f32 v[172:173], v[132:133], v[172:173]
	v_pk_mul_f32 v[174:175], v[134:135], v[174:175]
	s_mov_b64 exec, vcc
	v_pk_add_f32 v[212:213], v[160:161], v[168:169]
	v_pk_add_f32 v[214:215], v[162:163], v[170:171]
	v_pk_add_f32 v[216:217], v[164:165], v[172:173]
	v_pk_add_f32 v[218:219], v[166:167], v[174:175]
	s_mov_b64 exec, s[56:57]
	v_pk_add_f32 v[212:213], v[160:161], v[168:169] neg_lo:[0,1] neg_hi:[0,1]
	v_pk_add_f32 v[214:215], v[162:163], v[170:171] neg_lo:[0,1] neg_hi:[0,1]
	v_pk_add_f32 v[216:217], v[164:165], v[172:173] neg_lo:[0,1] neg_hi:[0,1]
	v_pk_add_f32 v[218:219], v[166:167], v[174:175] neg_lo:[0,1] neg_hi:[0,1]
	s_mov_b64 exec, s[100:101]
	v_cvt_pk_bf16_f32 v228, v212, v213
	v_cvt_pk_bf16_f32 v229, v214, v215
	v_cvt_pk_bf16_f32 v230, v216, v217
	v_cvt_pk_bf16_f32 v231, v218, v219
	global_store_dwordx4 v[140:141], v[228:231], off
	s_waitcnt lgkmcnt(0)
	v_mul_f32_e32 v189, s9, v189
	v_pk_mul_f32 v[212:213], v[100:101], v[188:189] op_sel:[0,1]
	v_pk_mul_f32 v[214:215], v[102:103], v[188:189] op_sel:[0,1]
	v_pk_mul_f32 v[216:217], v[88:89], v[188:189] op_sel:[0,1]
	v_pk_mul_f32 v[218:219], v[90:91], v[188:189] op_sel:[0,1]
	ds_bpermute_b32 v228, v0, v212
	ds_bpermute_b32 v229, v0, v213
	ds_bpermute_b32 v230, v0, v214
	ds_bpermute_b32 v231, v0, v215
	ds_bpermute_b32 v132, v0, v216
	ds_bpermute_b32 v133, v0, v217
	ds_bpermute_b32 v134, v0, v218
	ds_bpermute_b32 v135, v0, v219
	ds_read_b32 v188, v154 offset:128
	v_or_b32_e32 v143, 0x600, v159
	global_load_dwordx4 v[164:167], v143, s[20:21] offset:16
	global_load_dwordx4 v[160:163], v143, s[20:21]
	global_load_dwordx4 v[172:175], v143, s[22:23] offset:16
	global_load_dwordx4 v[168:171], v143, s[22:23]
	s_waitcnt lgkmcnt(1)
	s_waitcnt vmcnt(9)
	v_pk_mul_f32 v[176:177], v[212:213], v[176:177]
	v_pk_mul_f32 v[178:179], v[214:215], v[178:179]
	v_pk_mul_f32 v[180:181], v[216:217], v[180:181]
	v_pk_mul_f32 v[182:183], v[218:219], v[182:183]
	v_pk_mul_f32 v[184:185], v[228:229], v[184:185]
	v_pk_mul_f32 v[186:187], v[230:231], v[186:187]
	v_pk_mul_f32 v[190:191], v[132:133], v[190:191]
	v_pk_mul_f32 v[192:193], v[134:135], v[192:193]
	s_mov_b64 exec, vcc
	v_pk_add_f32 v[212:213], v[176:177], v[184:185]
	v_pk_add_f32 v[214:215], v[178:179], v[186:187]
	v_pk_add_f32 v[216:217], v[180:181], v[190:191]
	v_pk_add_f32 v[218:219], v[182:183], v[192:193]
	s_mov_b64 exec, s[56:57]
	v_pk_add_f32 v[212:213], v[176:177], v[184:185] neg_lo:[0,1] neg_hi:[0,1]
	v_pk_add_f32 v[214:215], v[178:179], v[186:187] neg_lo:[0,1] neg_hi:[0,1]
	v_pk_add_f32 v[216:217], v[180:181], v[190:191] neg_lo:[0,1] neg_hi:[0,1]
	v_pk_add_f32 v[218:219], v[182:183], v[192:193] neg_lo:[0,1] neg_hi:[0,1]
	s_mov_b64 exec, s[100:101]
	v_cvt_pk_bf16_f32 v228, v212, v213
	v_cvt_pk_bf16_f32 v229, v214, v215
	v_cvt_pk_bf16_f32 v230, v216, v217
	v_cvt_pk_bf16_f32 v231, v218, v219
	v_lshl_add_u64 v[132:133], v[140:141], 0, s[26:27]
	global_store_dwordx4 v[132:133], v[228:231], off
	s_waitcnt lgkmcnt(0)
	v_mul_f32_e32 v188, s9, v188
	v_pk_mul_f32 v[212:213], v[68:69], v[188:189] op_sel_hi:[1,0]
	v_pk_mul_f32 v[214:215], v[70:71], v[188:189] op_sel_hi:[1,0]
	v_pk_mul_f32 v[216:217], v[56:57], v[188:189] op_sel_hi:[1,0]
	v_pk_mul_f32 v[218:219], v[58:59], v[188:189] op_sel_hi:[1,0]
	ds_bpermute_b32 v228, v0, v212
	ds_bpermute_b32 v229, v0, v213
	ds_bpermute_b32 v230, v0, v214
	ds_bpermute_b32 v231, v0, v215
	ds_bpermute_b32 v132, v0, v216
	ds_bpermute_b32 v133, v0, v217
	ds_bpermute_b32 v134, v0, v218
	ds_bpermute_b32 v135, v0, v219
	ds_read_b32 v189, v154 offset:192
	v_mov_b32_e32 v159, 0x400
	v_lshl_add_u32 v159, v2, 3, v159
	v_and_b32_e32 v159, 0x3e78, v159
	v_lshlrev_b32_e32 v159, 2, v159
	global_load_dwordx4 v[180:183], v159, s[20:21] offset:16
	global_load_dwordx4 v[176:179], v159, s[20:21]
	global_load_dwordx4 v[190:193], v159, s[22:23] offset:16
	global_load_dwordx4 v[184:187], v159, s[22:23]
	s_waitcnt lgkmcnt(1)
; __device__ __forceinline__ u32x4 pack8(const float (&v)[8]) { u32x4 w; w.x = pk2(v[0], v[1]); w.y = pk2(v[2], v[3]); w.z = pk2(v[4], v[5]); w.w = pk2(v[6], v[7]); return w; }
;     __device__ __forceinline__ bool operator()(Acc& acc, const Unit& u, int wr, int wc, int fr, int fq, const LAS float* rstab) const {
;     ...
;                 if (rope) {
;                     const float sgn = (fq == 0) ? -1.f : 1.f;
; #pragma unroll
;                     for (int ai = 0; ai < 2; ++ai)
; #pragma unroll
;                         for (int m = 0; m < 4; ++m) {
;                             const float rs = rsp[ai * HALF + m * 16] * scale;
;                             const int pos = (rowb + ai * HALF + m * 16) & (SEQ - 1);
;                             const f32x4 c0 = gld<f32x4>(ropec + pos * 8), c1 = gld<f32x4>(ropec + pos * 8 + 4);
;                             const f32x4 s0 = gld<f32x4>(ropes + pos * 8), s1 = gld<f32x4>(ropes + pos * 8 + 4);
;                             float v[8];
; #pragma unroll
;                             for (int e = 0; e < 4; ++e) { v[e] = acc[ai][bj][m][0][e] * rs; v[4 + e] = acc[ai][bj][m][1][e] * rs; }
; #pragma unroll
;                             for (int e = 0; e < 8; ++e) {
;                                 const float p = __shfl_xor(v[e], 16);
;                                 const float cs = e < 4 ? c0[e & 3] : c1[e & 3], sn = e < 4 ? s0[e & 3] : s1[e & 3];
;                                 const float r = v[e] * cs + sgn * p * sn;
;                                 v[e] = (fq < 2) ? r : v[e];
;                             }
;                             gst<u32x4>(p0 + (ai * HALF + m * 16) * pitch, pack8(v));
;                             asm volatile("" ::: "memory");
;                         }
	s_waitcnt vmcnt(10)
	v_pk_mul_f32 v[194:195], v[212:213], v[194:195]
	v_pk_mul_f32 v[196:197], v[214:215], v[196:197]
	v_pk_mul_f32 v[200:201], v[216:217], v[200:201]
	v_pk_mul_f32 v[202:203], v[218:219], v[202:203]
	v_pk_mul_f32 v[206:207], v[228:229], v[206:207]
	v_pk_mul_f32 v[208:209], v[230:231], v[208:209]
	v_pk_mul_f32 v[220:221], v[132:133], v[220:221]
	v_pk_mul_f32 v[222:223], v[134:135], v[222:223]
	s_mov_b64 exec, vcc
	v_pk_add_f32 v[212:213], v[194:195], v[206:207]
	v_pk_add_f32 v[214:215], v[196:197], v[208:209]
	v_pk_add_f32 v[216:217], v[200:201], v[220:221]
	v_pk_add_f32 v[218:219], v[202:203], v[222:223]
	s_mov_b64 exec, s[56:57]
	v_pk_add_f32 v[212:213], v[194:195], v[206:207] neg_lo:[0,1] neg_hi:[0,1]
	v_pk_add_f32 v[214:215], v[196:197], v[208:209] neg_lo:[0,1] neg_hi:[0,1]
	v_pk_add_f32 v[216:217], v[200:201], v[220:221] neg_lo:[0,1] neg_hi:[0,1]
	v_pk_add_f32 v[218:219], v[202:203], v[222:223] neg_lo:[0,1] neg_hi:[0,1]
	s_mov_b64 exec, s[100:101]
	v_cvt_pk_bf16_f32 v228, v212, v213
	v_cvt_pk_bf16_f32 v229, v214, v215
	v_cvt_pk_bf16_f32 v230, v216, v217
	v_cvt_pk_bf16_f32 v231, v218, v219
	v_lshl_add_u64 v[132:133], s[26:27], 1, v[140:141]
	global_store_dwordx4 v[132:133], v[228:231], off
	s_lshl_b32 s26, s71, 8
	s_waitcnt lgkmcnt(0)
	v_mul_f32_e32 v189, s9, v189
	v_pk_mul_f32 v[212:213], v[36:37], v[188:189] op_sel:[0,1]
	v_pk_mul_f32 v[214:215], v[38:39], v[188:189] op_sel:[0,1]
	v_pk_mul_f32 v[216:217], v[28:29], v[188:189] op_sel:[0,1]
	v_pk_mul_f32 v[218:219], v[30:31], v[188:189] op_sel:[0,1]
	ds_bpermute_b32 v228, v0, v212
	ds_bpermute_b32 v229, v0, v213
	ds_bpermute_b32 v230, v0, v214
	ds_bpermute_b32 v231, v0, v215
	ds_bpermute_b32 v132, v0, v216
	ds_bpermute_b32 v133, v0, v217
	ds_bpermute_b32 v134, v0, v218
	ds_bpermute_b32 v135, v0, v219
	ds_read_b32 v188, v154 offset:512
	v_or_b32_e32 v143, 0x200, v159
	global_load_dwordx4 v[200:203], v143, s[20:21] offset:16
	global_load_dwordx4 v[194:197], v143, s[20:21]
	global_load_dwordx4 v[220:223], v143, s[22:23] offset:16
	global_load_dwordx4 v[206:209], v143, s[22:23]
	s_waitcnt lgkmcnt(1)
	s_waitcnt vmcnt(10)
	v_pk_mul_f32 v[160:161], v[212:213], v[160:161]
	v_pk_mul_f32 v[162:163], v[214:215], v[162:163]
	v_pk_mul_f32 v[164:165], v[216:217], v[164:165]
	v_pk_mul_f32 v[166:167], v[218:219], v[166:167]
	v_pk_mul_f32 v[168:169], v[228:229], v[168:169]
	v_pk_mul_f32 v[170:171], v[230:231], v[170:171]
	v_pk_mul_f32 v[172:173], v[132:133], v[172:173]
	v_pk_mul_f32 v[174:175], v[134:135], v[174:175]
	s_mov_b64 exec, vcc
	v_pk_add_f32 v[212:213], v[160:161], v[168:169]
	v_pk_add_f32 v[214:215], v[162:163], v[170:171]
	v_pk_add_f32 v[216:217], v[164:165], v[172:173]
	v_pk_add_f32 v[218:219], v[166:167], v[174:175]
	s_mov_b64 exec, s[56:57]
	v_pk_add_f32 v[212:213], v[160:161], v[168:169] neg_lo:[0,1] neg_hi:[0,1]
	v_pk_add_f32 v[214:215], v[162:163], v[170:171] neg_lo:[0,1] neg_hi:[0,1]
	v_pk_add_f32 v[216:217], v[164:165], v[172:173] neg_lo:[0,1] neg_hi:[0,1]
	v_pk_add_f32 v[218:219], v[166:167], v[174:175] neg_lo:[0,1] neg_hi:[0,1]
	s_mov_b64 exec, s[100:101]
	v_cvt_pk_bf16_f32 v228, v212, v213
	v_cvt_pk_bf16_f32 v229, v214, v215
	v_cvt_pk_bf16_f32 v230, v216, v217
	v_cvt_pk_bf16_f32 v231, v218, v219
	v_lshl_add_u64 v[132:133], s[58:59], 1, v[140:141]
	global_store_dwordx4 v[132:133], v[228:231], off
	s_waitcnt lgkmcnt(0)
	v_mul_f32_e32 v188, s9, v188
	v_pk_mul_f32 v[212:213], v[72:73], v[188:189] op_sel_hi:[1,0]
	v_pk_mul_f32 v[214:215], v[74:75], v[188:189] op_sel_hi:[1,0]
	v_pk_mul_f32 v[216:217], v[60:61], v[188:189] op_sel_hi:[1,0]
	v_pk_mul_f32 v[218:219], v[62:63], v[188:189] op_sel_hi:[1,0]
	ds_bpermute_b32 v228, v0, v212
	ds_bpermute_b32 v229, v0, v213
	ds_bpermute_b32 v230, v0, v214
	ds_bpermute_b32 v231, v0, v215
	ds_bpermute_b32 v132, v0, v216
	ds_bpermute_b32 v133, v0, v217
	ds_bpermute_b32 v134, v0, v218
	ds_bpermute_b32 v135, v0, v219
	ds_read_b32 v189, v154 offset:576
	v_or_b32_e32 v143, 0x400, v159
	global_load_dwordx4 v[164:167], v143, s[20:21] offset:16
	global_load_dwordx4 v[160:163], v143, s[20:21]
	global_load_dwordx4 v[172:175], v143, s[22:23] offset:16
	global_load_dwordx4 v[168:171], v143, s[22:23]
	s_waitcnt lgkmcnt(1)
	s_waitcnt vmcnt(10)
	v_pk_mul_f32 v[176:177], v[212:213], v[176:177]
	v_pk_mul_f32 v[178:179], v[214:215], v[178:179]
	v_pk_mul_f32 v[180:181], v[216:217], v[180:181]
	v_pk_mul_f32 v[182:183], v[218:219], v[182:183]
	v_pk_mul_f32 v[184:185], v[228:229], v[184:185]
	v_pk_mul_f32 v[186:187], v[230:231], v[186:187]
	v_pk_mul_f32 v[190:191], v[132:133], v[190:191]
	v_pk_mul_f32 v[192:193], v[134:135], v[192:193]
	s_mov_b64 exec, vcc
	v_pk_add_f32 v[212:213], v[176:177], v[184:185]
	v_pk_add_f32 v[214:215], v[178:179], v[186:187]
	v_pk_add_f32 v[216:217], v[180:181], v[190:191]
	v_pk_add_f32 v[218:219], v[182:183], v[192:193]
	s_mov_b64 exec, s[56:57]
	v_pk_add_f32 v[212:213], v[176:177], v[184:185] neg_lo:[0,1] neg_hi:[0,1]
	v_pk_add_f32 v[214:215], v[178:179], v[186:187] neg_lo:[0,1] neg_hi:[0,1]
	v_pk_add_f32 v[216:217], v[180:181], v[190:191] neg_lo:[0,1] neg_hi:[0,1]
	v_pk_add_f32 v[218:219], v[182:183], v[192:193] neg_lo:[0,1] neg_hi:[0,1]
	s_mov_b64 exec, s[100:101]
	v_cvt_pk_bf16_f32 v228, v212, v213
	v_cvt_pk_bf16_f32 v229, v214, v215
	v_cvt_pk_bf16_f32 v230, v216, v217
	v_cvt_pk_bf16_f32 v231, v218, v219
	v_lshl_add_u64 v[132:133], v[140:141], 0, s[26:27]
	global_store_dwordx4 v[132:133], v[228:231], off
	s_waitcnt lgkmcnt(0)
; __device__ __forceinline__ u32x4 pack8(const float (&v)[8]) { u32x4 w; w.x = pk2(v[0], v[1]); w.y = pk2(v[2], v[3]); w.z = pk2(v[4], v[5]); w.w = pk2(v[6], v[7]); return w; }
;     __device__ __forceinline__ bool operator()(Acc& acc, const Unit& u, int wr, int wc, int fr, int fq, const LAS float* rstab) const {
;     ...
;                 if (rope) {
;                     const float sgn = (fq == 0) ? -1.f : 1.f;
; #pragma unroll
;                     for (int ai = 0; ai < 2; ++ai)
; #pragma unroll
;                         for (int m = 0; m < 4; ++m) {
;                             const float rs = rsp[ai * HALF + m * 16] * scale;
;                             const int pos = (rowb + ai * HALF + m * 16) & (SEQ - 1);
;                             const f32x4 c0 = gld<f32x4>(ropec + pos * 8), c1 = gld<f32x4>(ropec + pos * 8 + 4);
;                             const f32x4 s0 = gld<f32x4>(ropes + pos * 8), s1 = gld<f32x4>(ropes + pos * 8 + 4);
;                             float v[8];
; #pragma unroll
;                             for (int e = 0; e < 4; ++e) { v[e] = acc[ai][bj][m][0][e] * rs; v[4 + e] = acc[ai][bj][m][1][e] * rs; }
; #pragma unroll
;                             for (int e = 0; e < 8; ++e) {
;                                 const float p = __shfl_xor(v[e], 16);
;                                 const float cs = e < 4 ? c0[e & 3] : c1[e & 3], sn = e < 4 ? s0[e & 3] : s1[e & 3];
;                                 const float r = v[e] * cs + sgn * p * sn;
;                                 v[e] = (fq < 2) ? r : v[e];
;                             }
;                             gst<u32x4>(p0 + (ai * HALF + m * 16) * pitch, pack8(v));
;                             asm volatile("" ::: "memory");
;                         }
	v_mul_f32_e32 v189, s9, v189
	v_pk_mul_f32 v[212:213], v[40:41], v[188:189] op_sel:[0,1]
	v_pk_mul_f32 v[214:215], v[42:43], v[188:189] op_sel:[0,1]
	v_pk_mul_f32 v[216:217], v[32:33], v[188:189] op_sel:[0,1]
	v_pk_mul_f32 v[218:219], v[34:35], v[188:189] op_sel:[0,1]
	ds_bpermute_b32 v228, v0, v212
	ds_bpermute_b32 v229, v0, v213
	ds_bpermute_b32 v230, v0, v214
	ds_bpermute_b32 v231, v0, v215
	ds_bpermute_b32 v132, v0, v216
	ds_bpermute_b32 v133, v0, v217
	ds_bpermute_b32 v134, v0, v218
	ds_bpermute_b32 v135, v0, v219
	ds_read_b32 v188, v154 offset:640
	v_or_b32_e32 v143, 0x600, v159
	global_load_dwordx4 v[180:183], v143, s[20:21] offset:16
	global_load_dwordx4 v[176:179], v143, s[20:21]
	global_load_dwordx4 v[190:193], v143, s[22:23] offset:16
	global_load_dwordx4 v[184:187], v143, s[22:23]
	s_waitcnt lgkmcnt(1)
	s_waitcnt vmcnt(10)
	v_pk_mul_f32 v[194:195], v[212:213], v[194:195]
	v_pk_mul_f32 v[196:197], v[214:215], v[196:197]
	v_pk_mul_f32 v[200:201], v[216:217], v[200:201]
	v_pk_mul_f32 v[202:203], v[218:219], v[202:203]
	v_pk_mul_f32 v[206:207], v[228:229], v[206:207]
	v_pk_mul_f32 v[208:209], v[230:231], v[208:209]
	v_pk_mul_f32 v[220:221], v[132:133], v[220:221]
	v_pk_mul_f32 v[222:223], v[134:135], v[222:223]
	s_mov_b64 exec, vcc
	v_pk_add_f32 v[212:213], v[194:195], v[206:207]
	v_pk_add_f32 v[214:215], v[196:197], v[208:209]
	v_pk_add_f32 v[216:217], v[200:201], v[220:221]
	v_pk_add_f32 v[218:219], v[202:203], v[222:223]
	s_mov_b64 exec, s[56:57]
	v_pk_add_f32 v[212:213], v[194:195], v[206:207] neg_lo:[0,1] neg_hi:[0,1]
	v_pk_add_f32 v[214:215], v[196:197], v[208:209] neg_lo:[0,1] neg_hi:[0,1]
	v_pk_add_f32 v[216:217], v[200:201], v[220:221] neg_lo:[0,1] neg_hi:[0,1]
	v_pk_add_f32 v[218:219], v[202:203], v[222:223] neg_lo:[0,1] neg_hi:[0,1]
	s_mov_b64 exec, s[100:101]
	v_cvt_pk_bf16_f32 v228, v212, v213
	v_cvt_pk_bf16_f32 v229, v214, v215
	v_cvt_pk_bf16_f32 v230, v216, v217
	v_cvt_pk_bf16_f32 v231, v218, v219
	v_lshl_add_u64 v[132:133], s[18:19], 1, v[140:141]
	global_store_dwordx4 v[132:133], v[228:231], off
	s_waitcnt lgkmcnt(0)
	v_mul_f32_e32 v188, s9, v188
	v_pk_mul_f32 v[212:213], v[16:17], v[188:189] op_sel_hi:[1,0]
	v_pk_mul_f32 v[214:215], v[18:19], v[188:189] op_sel_hi:[1,0]
	v_pk_mul_f32 v[216:217], v[12:13], v[188:189] op_sel_hi:[1,0]
	v_pk_mul_f32 v[218:219], v[14:15], v[188:189] op_sel_hi:[1,0]
	ds_bpermute_b32 v228, v0, v212
	ds_bpermute_b32 v229, v0, v213
	ds_bpermute_b32 v230, v0, v214
	ds_bpermute_b32 v231, v0, v215
	ds_bpermute_b32 v132, v0, v216
	ds_bpermute_b32 v133, v0, v217
	ds_bpermute_b32 v134, v0, v218
	ds_bpermute_b32 v135, v0, v219
	ds_read_b32 v189, v154 offset:704
	s_waitcnt lgkmcnt(1)
	s_waitcnt vmcnt(6)
	v_pk_mul_f32 v[160:161], v[212:213], v[160:161]
	v_pk_mul_f32 v[162:163], v[214:215], v[162:163]
	v_pk_mul_f32 v[164:165], v[216:217], v[164:165]
	v_pk_mul_f32 v[166:167], v[218:219], v[166:167]
	v_pk_mul_f32 v[168:169], v[228:229], v[168:169]
	v_pk_mul_f32 v[170:171], v[230:231], v[170:171]
	v_pk_mul_f32 v[172:173], v[132:133], v[172:173]
	v_pk_mul_f32 v[174:175], v[134:135], v[174:175]
	s_mov_b64 exec, vcc
	v_pk_add_f32 v[212:213], v[160:161], v[168:169]
	v_pk_add_f32 v[214:215], v[162:163], v[170:171]
	v_pk_add_f32 v[216:217], v[164:165], v[172:173]
	v_pk_add_f32 v[218:219], v[166:167], v[174:175]
	s_mov_b64 exec, s[56:57]
	v_pk_add_f32 v[212:213], v[160:161], v[168:169] neg_lo:[0,1] neg_hi:[0,1]
	v_pk_add_f32 v[214:215], v[162:163], v[170:171] neg_lo:[0,1] neg_hi:[0,1]
	v_pk_add_f32 v[216:217], v[164:165], v[172:173] neg_lo:[0,1] neg_hi:[0,1]
	v_pk_add_f32 v[218:219], v[166:167], v[174:175] neg_lo:[0,1] neg_hi:[0,1]
	s_mov_b64 exec, s[100:101]
	v_cvt_pk_bf16_f32 v228, v212, v213
	v_cvt_pk_bf16_f32 v229, v214, v215
	v_cvt_pk_bf16_f32 v230, v216, v217
	v_cvt_pk_bf16_f32 v231, v218, v219
	v_lshl_add_u64 v[132:133], s[16:17], 1, v[140:141]
	global_store_dwordx4 v[132:133], v[228:231], off
	s_waitcnt lgkmcnt(0)
	v_mul_f32_e32 v189, s9, v189
	v_pk_mul_f32 v[212:213], v[8:9], v[188:189] op_sel:[0,1]
	v_pk_mul_f32 v[214:215], v[10:11], v[188:189] op_sel:[0,1]
	v_pk_mul_f32 v[216:217], v[4:5], v[188:189] op_sel:[0,1]
	v_pk_mul_f32 v[218:219], v[6:7], v[188:189] op_sel:[0,1]
	ds_bpermute_b32 v228, v0, v212
	ds_bpermute_b32 v229, v0, v213
	ds_bpermute_b32 v230, v0, v214
	ds_bpermute_b32 v231, v0, v215
	ds_bpermute_b32 v132, v0, v216
	ds_bpermute_b32 v133, v0, v217
	ds_bpermute_b32 v134, v0, v218
	ds_bpermute_b32 v135, v0, v219
	s_waitcnt lgkmcnt(0)
	s_waitcnt vmcnt(2)
	v_pk_mul_f32 v[176:177], v[212:213], v[176:177]
	v_pk_mul_f32 v[178:179], v[214:215], v[178:179]
	v_pk_mul_f32 v[180:181], v[216:217], v[180:181]
	v_pk_mul_f32 v[182:183], v[218:219], v[182:183]
	v_pk_mul_f32 v[184:185], v[228:229], v[184:185]
	v_pk_mul_f32 v[186:187], v[230:231], v[186:187]
	v_pk_mul_f32 v[190:191], v[132:133], v[190:191]
	v_pk_mul_f32 v[192:193], v[134:135], v[192:193]
	s_mov_b64 exec, vcc
	v_pk_add_f32 v[212:213], v[176:177], v[184:185]
	v_pk_add_f32 v[214:215], v[178:179], v[186:187]
	v_pk_add_f32 v[216:217], v[180:181], v[190:191]
	v_pk_add_f32 v[218:219], v[182:183], v[192:193]
	s_mov_b64 exec, s[56:57]
	v_pk_add_f32 v[212:213], v[176:177], v[184:185] neg_lo:[0,1] neg_hi:[0,1]
	v_pk_add_f32 v[214:215], v[178:179], v[186:187] neg_lo:[0,1] neg_hi:[0,1]
	v_pk_add_f32 v[216:217], v[180:181], v[190:191] neg_lo:[0,1] neg_hi:[0,1]
	v_pk_add_f32 v[218:219], v[182:183], v[192:193] neg_lo:[0,1] neg_hi:[0,1]
	s_mov_b64 exec, s[100:101]
	v_cvt_pk_bf16_f32 v228, v212, v213
	v_cvt_pk_bf16_f32 v229, v214, v215
	v_cvt_pk_bf16_f32 v230, v216, v217
	v_cvt_pk_bf16_f32 v231, v218, v219
	v_lshl_add_u64 v[132:133], s[14:15], 1, v[140:141]
	global_store_dwordx4 v[132:133], v[228:231], off

; __device__ __forceinline__ u32x4 pack8(const float (&v)[8]) { u32x4 w; w.x = pk2(v[0], v[1]); w.y = pk2(v[2], v[3]); w.z = pk2(v[4], v[5]); w.w = pk2(v[6], v[7]); return w; }
;     __device__ __forceinline__ bool operator()(Acc& acc, const Unit& u, int wr, int wc, int fr, int fq, const LAS float* rstab) const {
;     ...
;                 if (rope) {
;                     const float sgn = (fq == 0) ? -1.f : 1.f;
; #pragma unroll
;                     for (int ai = 0; ai < 2; ++ai)
; #pragma unroll
;                         for (int m = 0; m < 4; ++m) {
;                             const float rs = rsp[ai * HALF + m * 16] * scale;
;                             const int pos = (rowb + ai * HALF + m * 16) & (SEQ - 1);
;                             const f32x4 c0 = gld<f32x4>(ropec + pos * 8), c1 = gld<f32x4>(ropec + pos * 8 + 4);
;                             const f32x4 s0 = gld<f32x4>(ropes + pos * 8), s1 = gld<f32x4>(ropes + pos * 8 + 4);
;                             float v[8];
; #pragma unroll
;                             for (int e = 0; e < 4; ++e) { v[e] = acc[ai][bj][m][0][e] * rs; v[4 + e] = acc[ai][bj][m][1][e] * rs; }
; #pragma unroll
;                             for (int e = 0; e < 8; ++e) {
;                                 const float p = __shfl_xor(v[e], 16);
;                                 const float cs = e < 4 ? c0[e & 3] : c1[e & 3], sn = e < 4 ? s0[e & 3] : s1[e & 3];
;                                 const float r = v[e] * cs + sgn * p * sn;
;                                 v[e] = (fq < 2) ? r : v[e];
;                             }
;                             gst<u32x4>(p0 + (ai * HALF + m * 16) * pitch, pack8(v));
;                             asm volatile("" ::: "memory");
;                         }
.LBB0_450:
	s_andn2_b64 vcc, exec, s[58:59]
	s_cbranch_vccnz .LBB0_452
	v_and_b32_e32 v132, 64, v198
	v_xor_b32_e32 v0, 16, v198
	v_add_u32_e32 v132, 64, v132
	v_cmp_lt_i32_e32 vcc, v0, v132
	s_lshl_b32 s26, s61, 5
	s_mov_b32 s19, s27
	s_mov_b32 s17, s27
	s_mov_b32 s15, s27
	s_mov_b32 s13, s27
	v_cndmask_b32_e32 v0, v198, v0, vcc
	v_lshlrev_b32_e32 v0, 2, v0
	s_mov_b64 s[100:101], exec
	s_andn2_b64 vcc, s[54:55], s[56:57]
	ds_read_b32 v188, v154
	v_lshlrev_b32_e32 v159, 5, v2
	v_and_b32_e32 v159, 0xf9e0, v159
	global_load_dwordx4 v[164:167], v159, s[20:21] offset:16
	global_load_dwordx4 v[160:163], v159, s[20:21]
	global_load_dwordx4 v[172:175], v159, s[22:23] offset:16
	global_load_dwordx4 v[168:171], v159, s[22:23]
	v_or_b32_e32 v136, 0x200, v159
	global_load_dwordx4 v[180:183], v136, s[20:21] offset:16
	global_load_dwordx4 v[176:179], v136, s[20:21]
	global_load_dwordx4 v[190:193], v136, s[22:23] offset:16
	global_load_dwordx4 v[184:187], v136, s[22:23]
	s_waitcnt lgkmcnt(0)
	v_mul_f32_e32 v188, s9, v188
	v_pk_mul_f32 v[212:213], v[128:129], v[188:189] op_sel_hi:[1,0]
	v_pk_mul_f32 v[214:215], v[130:131], v[188:189] op_sel_hi:[1,0]
	v_pk_mul_f32 v[216:217], v[124:125], v[188:189] op_sel_hi:[1,0]
	v_pk_mul_f32 v[218:219], v[126:127], v[188:189] op_sel_hi:[1,0]
	ds_bpermute_b32 v228, v0, v212
	ds_bpermute_b32 v229, v0, v213
	ds_bpermute_b32 v230, v0, v214
	ds_bpermute_b32 v231, v0, v215
	ds_bpermute_b32 v132, v0, v216
	ds_bpermute_b32 v133, v0, v217
	ds_bpermute_b32 v134, v0, v218
	ds_bpermute_b32 v135, v0, v219
	ds_read_b32 v189, v154 offset:64
	v_or_b32_e32 v136, 0x400, v159
	global_load_dwordx4 v[200:203], v136, s[20:21] offset:16
	global_load_dwordx4 v[194:197], v136, s[20:21]
	global_load_dwordx4 v[220:223], v136, s[22:23] offset:16
	global_load_dwordx4 v[206:209], v136, s[22:23]
	s_waitcnt lgkmcnt(1)
	s_waitcnt vmcnt(8)
	v_pk_mul_f32 v[160:161], v[212:213], v[160:161]
	v_pk_mul_f32 v[162:163], v[214:215], v[162:163]
	v_pk_mul_f32 v[164:165], v[216:217], v[164:165]
	v_pk_mul_f32 v[166:167], v[218:219], v[166:167]
	v_pk_mul_f32 v[168:169], v[228:229], v[168:169]
	v_pk_mul_f32 v[170:171], v[230:231], v[170:171]
	v_pk_mul_f32 v[172:173], v[132:133], v[172:173]
	v_pk_mul_f32 v[174:175], v[134:135], v[174:175]
	s_mov_b64 exec, vcc
	v_pk_add_f32 v[212:213], v[160:161], v[168:169]
	v_pk_add_f32 v[214:215], v[162:163], v[170:171]
	v_pk_add_f32 v[216:217], v[164:165], v[172:173]
	v_pk_add_f32 v[218:219], v[166:167], v[174:175]
	s_mov_b64 exec, s[56:57]
	v_pk_add_f32 v[212:213], v[160:161], v[168:169] neg_lo:[0,1] neg_hi:[0,1]
	v_pk_add_f32 v[214:215], v[162:163], v[170:171] neg_lo:[0,1] neg_hi:[0,1]
	v_pk_add_f32 v[216:217], v[164:165], v[172:173] neg_lo:[0,1] neg_hi:[0,1]
	v_pk_add_f32 v[218:219], v[166:167], v[174:175] neg_lo:[0,1] neg_hi:[0,1]
	s_mov_b64 exec, s[100:101]
	v_cvt_pk_bf16_f32 v228, v212, v213
	v_cvt_pk_bf16_f32 v229, v214, v215
	v_cvt_pk_bf16_f32 v230, v216, v217
	v_cvt_pk_bf16_f32 v231, v218, v219
	global_store_dwordx4 v[142:143], v[228:231], off
	s_waitcnt lgkmcnt(0)
	v_mul_f32_e32 v189, s9, v189
	v_pk_mul_f32 v[212:213], v[116:117], v[188:189] op_sel:[0,1]
	v_pk_mul_f32 v[214:215], v[118:119], v[188:189] op_sel:[0,1]
	v_pk_mul_f32 v[216:217], v[108:109], v[188:189] op_sel:[0,1]
	v_pk_mul_f32 v[218:219], v[110:111], v[188:189] op_sel:[0,1]
	ds_bpermute_b32 v228, v0, v212
	ds_bpermute_b32 v229, v0, v213
	ds_bpermute_b32 v230, v0, v214
	ds_bpermute_b32 v231, v0, v215
	ds_bpermute_b32 v132, v0, v216
	ds_bpermute_b32 v133, v0, v217
	ds_bpermute_b32 v134, v0, v218
	ds_bpermute_b32 v135, v0, v219
	ds_read_b32 v188, v154 offset:128
	v_or_b32_e32 v136, 0x600, v159
	global_load_dwordx4 v[164:167], v136, s[20:21] offset:16
	global_load_dwordx4 v[160:163], v136, s[20:21]
	global_load_dwordx4 v[172:175], v136, s[22:23] offset:16
	global_load_dwordx4 v[168:171], v136, s[22:23]
	s_waitcnt lgkmcnt(1)
	s_waitcnt vmcnt(9)
	v_pk_mul_f32 v[176:177], v[212:213], v[176:177]
	v_pk_mul_f32 v[178:179], v[214:215], v[178:179]
	v_pk_mul_f32 v[180:181], v[216:217], v[180:181]
	v_pk_mul_f32 v[182:183], v[218:219], v[182:183]
	v_pk_mul_f32 v[184:185], v[228:229], v[184:185]
	v_pk_mul_f32 v[186:187], v[230:231], v[186:187]
	v_pk_mul_f32 v[190:191], v[132:133], v[190:191]
	v_pk_mul_f32 v[192:193], v[134:135], v[192:193]
	s_mov_b64 exec, vcc
	v_pk_add_f32 v[212:213], v[176:177], v[184:185]
	v_pk_add_f32 v[214:215], v[178:179], v[186:187]
	v_pk_add_f32 v[216:217], v[180:181], v[190:191]
	v_pk_add_f32 v[218:219], v[182:183], v[192:193]
	s_mov_b64 exec, s[56:57]
	v_pk_add_f32 v[212:213], v[176:177], v[184:185] neg_lo:[0,1] neg_hi:[0,1]
	v_pk_add_f32 v[214:215], v[178:179], v[186:187] neg_lo:[0,1] neg_hi:[0,1]
	v_pk_add_f32 v[216:217], v[180:181], v[190:191] neg_lo:[0,1] neg_hi:[0,1]
	v_pk_add_f32 v[218:219], v[182:183], v[192:193] neg_lo:[0,1] neg_hi:[0,1]
	s_mov_b64 exec, s[100:101]
	v_cvt_pk_bf16_f32 v228, v212, v213
	v_cvt_pk_bf16_f32 v229, v214, v215
	v_cvt_pk_bf16_f32 v230, v216, v217
	v_cvt_pk_bf16_f32 v231, v218, v219
	v_lshl_add_u64 v[132:133], v[142:143], 0, s[26:27]
	global_store_dwordx4 v[132:133], v[228:231], off
	s_waitcnt lgkmcnt(0)
	v_mul_f32_e32 v188, s9, v188
	v_pk_mul_f32 v[212:213], v[92:93], v[188:189] op_sel_hi:[1,0]
	v_pk_mul_f32 v[214:215], v[94:95], v[188:189] op_sel_hi:[1,0]
	v_pk_mul_f32 v[216:217], v[80:81], v[188:189] op_sel_hi:[1,0]
	v_pk_mul_f32 v[218:219], v[82:83], v[188:189] op_sel_hi:[1,0]
	ds_bpermute_b32 v228, v0, v212
	ds_bpermute_b32 v229, v0, v213
	ds_bpermute_b32 v230, v0, v214
	ds_bpermute_b32 v231, v0, v215
	ds_bpermute_b32 v132, v0, v216
	ds_bpermute_b32 v133, v0, v217
	ds_bpermute_b32 v134, v0, v218
	ds_bpermute_b32 v135, v0, v219
	ds_read_b32 v189, v154 offset:192
	v_mov_b32_e32 v159, 0x400
	v_lshl_add_u32 v159, v2, 3, v159
	v_and_b32_e32 v159, 0x3e78, v159
	v_lshlrev_b32_e32 v159, 2, v159
	global_load_dwordx4 v[180:183], v159, s[20:21] offset:16
	global_load_dwordx4 v[176:179], v159, s[20:21]
	global_load_dwordx4 v[190:193], v159, s[22:23] offset:16
	global_load_dwordx4 v[184:187], v159, s[22:23]
	s_waitcnt lgkmcnt(1)
; __device__ __forceinline__ u32x4 pack8(const float (&v)[8]) { u32x4 w; w.x = pk2(v[0], v[1]); w.y = pk2(v[2], v[3]); w.z = pk2(v[4], v[5]); w.w = pk2(v[6], v[7]); return w; }
;     __device__ __forceinline__ bool operator()(Acc& acc, const Unit& u, int wr, int wc, int fr, int fq, const LAS float* rstab) const {
;     ...
;                 if (rope) {
;                     const float sgn = (fq == 0) ? -1.f : 1.f;
; #pragma unroll
;                     for (int ai = 0; ai < 2; ++ai)
; #pragma unroll
;                         for (int m = 0; m < 4; ++m) {
;                             const float rs = rsp[ai * HALF + m * 16] * scale;
;                             const int pos = (rowb + ai * HALF + m * 16) & (SEQ - 1);
;                             const f32x4 c0 = gld<f32x4>(ropec + pos * 8), c1 = gld<f32x4>(ropec + pos * 8 + 4);
;                             const f32x4 s0 = gld<f32x4>(ropes + pos * 8), s1 = gld<f32x4>(ropes + pos * 8 + 4);
;                             float v[8];
; #pragma unroll
;                             for (int e = 0; e < 4; ++e) { v[e] = acc[ai][bj][m][0][e] * rs; v[4 + e] = acc[ai][bj][m][1][e] * rs; }
; #pragma unroll
;                             for (int e = 0; e < 8; ++e) {
;                                 const float p = __shfl_xor(v[e], 16);
;                                 const float cs = e < 4 ? c0[e & 3] : c1[e & 3], sn = e < 4 ? s0[e & 3] : s1[e & 3];
;                                 const float r = v[e] * cs + sgn * p * sn;
;                                 v[e] = (fq < 2) ? r : v[e];
;                             }
;                             gst<u32x4>(p0 + (ai * HALF + m * 16) * pitch, pack8(v));
;                             asm volatile("" ::: "memory");
;                         }
	s_waitcnt vmcnt(10)
	v_pk_mul_f32 v[194:195], v[212:213], v[194:195]
	v_pk_mul_f32 v[196:197], v[214:215], v[196:197]
	v_pk_mul_f32 v[200:201], v[216:217], v[200:201]
	v_pk_mul_f32 v[202:203], v[218:219], v[202:203]
	v_pk_mul_f32 v[206:207], v[228:229], v[206:207]
	v_pk_mul_f32 v[208:209], v[230:231], v[208:209]
	v_pk_mul_f32 v[220:221], v[132:133], v[220:221]
	v_pk_mul_f32 v[222:223], v[134:135], v[222:223]
	s_mov_b64 exec, vcc
	v_pk_add_f32 v[212:213], v[194:195], v[206:207]
	v_pk_add_f32 v[214:215], v[196:197], v[208:209]
	v_pk_add_f32 v[216:217], v[200:201], v[220:221]
	v_pk_add_f32 v[218:219], v[202:203], v[222:223]
	s_mov_b64 exec, s[56:57]
	v_pk_add_f32 v[212:213], v[194:195], v[206:207] neg_lo:[0,1] neg_hi:[0,1]
	v_pk_add_f32 v[214:215], v[196:197], v[208:209] neg_lo:[0,1] neg_hi:[0,1]
	v_pk_add_f32 v[216:217], v[200:201], v[220:221] neg_lo:[0,1] neg_hi:[0,1]
	v_pk_add_f32 v[218:219], v[202:203], v[222:223] neg_lo:[0,1] neg_hi:[0,1]
	s_mov_b64 exec, s[100:101]
	v_cvt_pk_bf16_f32 v228, v212, v213
	v_cvt_pk_bf16_f32 v229, v214, v215
	v_cvt_pk_bf16_f32 v230, v216, v217
	v_cvt_pk_bf16_f32 v231, v218, v219
	v_lshl_add_u64 v[132:133], s[26:27], 1, v[142:143]
	global_store_dwordx4 v[132:133], v[228:231], off
	s_lshl_b32 s26, s61, 8
	s_waitcnt lgkmcnt(0)
	v_mul_f32_e32 v189, s9, v189
	v_pk_mul_f32 v[212:213], v[64:65], v[188:189] op_sel:[0,1]
	v_pk_mul_f32 v[214:215], v[66:67], v[188:189] op_sel:[0,1]
	v_pk_mul_f32 v[216:217], v[48:49], v[188:189] op_sel:[0,1]
	v_pk_mul_f32 v[218:219], v[50:51], v[188:189] op_sel:[0,1]
	ds_bpermute_b32 v228, v0, v212
	ds_bpermute_b32 v229, v0, v213
	ds_bpermute_b32 v230, v0, v214
	ds_bpermute_b32 v231, v0, v215
	ds_bpermute_b32 v132, v0, v216
	ds_bpermute_b32 v133, v0, v217
	ds_bpermute_b32 v134, v0, v218
	ds_bpermute_b32 v135, v0, v219
	ds_read_b32 v188, v154 offset:512
	v_or_b32_e32 v136, 0x200, v159
	global_load_dwordx4 v[200:203], v136, s[20:21] offset:16
	global_load_dwordx4 v[194:197], v136, s[20:21]
	global_load_dwordx4 v[220:223], v136, s[22:23] offset:16
	global_load_dwordx4 v[206:209], v136, s[22:23]
	s_waitcnt lgkmcnt(1)
	s_waitcnt vmcnt(10)
	v_pk_mul_f32 v[160:161], v[212:213], v[160:161]
	v_pk_mul_f32 v[162:163], v[214:215], v[162:163]
	v_pk_mul_f32 v[164:165], v[216:217], v[164:165]
	v_pk_mul_f32 v[166:167], v[218:219], v[166:167]
	v_pk_mul_f32 v[168:169], v[228:229], v[168:169]
	v_pk_mul_f32 v[170:171], v[230:231], v[170:171]
	v_pk_mul_f32 v[172:173], v[132:133], v[172:173]
	v_pk_mul_f32 v[174:175], v[134:135], v[174:175]
	s_mov_b64 exec, vcc
	v_pk_add_f32 v[212:213], v[160:161], v[168:169]
	v_pk_add_f32 v[214:215], v[162:163], v[170:171]
	v_pk_add_f32 v[216:217], v[164:165], v[172:173]
	v_pk_add_f32 v[218:219], v[166:167], v[174:175]
	s_mov_b64 exec, s[56:57]
	v_pk_add_f32 v[212:213], v[160:161], v[168:169] neg_lo:[0,1] neg_hi:[0,1]
	v_pk_add_f32 v[214:215], v[162:163], v[170:171] neg_lo:[0,1] neg_hi:[0,1]
	v_pk_add_f32 v[216:217], v[164:165], v[172:173] neg_lo:[0,1] neg_hi:[0,1]
	v_pk_add_f32 v[218:219], v[166:167], v[174:175] neg_lo:[0,1] neg_hi:[0,1]
	s_mov_b64 exec, s[100:101]
	v_cvt_pk_bf16_f32 v228, v212, v213
	v_cvt_pk_bf16_f32 v229, v214, v215
	v_cvt_pk_bf16_f32 v230, v216, v217
	v_cvt_pk_bf16_f32 v231, v218, v219
	v_lshl_add_u64 v[132:133], s[18:19], 1, v[142:143]
	global_store_dwordx4 v[132:133], v[228:231], off
	s_waitcnt lgkmcnt(0)
	v_mul_f32_e32 v188, s9, v188
	v_pk_mul_f32 v[212:213], v[96:97], v[188:189] op_sel_hi:[1,0]
	v_pk_mul_f32 v[214:215], v[98:99], v[188:189] op_sel_hi:[1,0]
	v_pk_mul_f32 v[216:217], v[104:105], v[188:189] op_sel_hi:[1,0]
	v_pk_mul_f32 v[218:219], v[106:107], v[188:189] op_sel_hi:[1,0]
	ds_bpermute_b32 v228, v0, v212
	ds_bpermute_b32 v229, v0, v213
	ds_bpermute_b32 v230, v0, v214
	ds_bpermute_b32 v231, v0, v215
	ds_bpermute_b32 v132, v0, v216
	ds_bpermute_b32 v133, v0, v217
	ds_bpermute_b32 v134, v0, v218
	ds_bpermute_b32 v135, v0, v219
	ds_read_b32 v189, v154 offset:576
	v_or_b32_e32 v136, 0x400, v159
	global_load_dwordx4 v[164:167], v136, s[20:21] offset:16
	global_load_dwordx4 v[160:163], v136, s[20:21]
	global_load_dwordx4 v[172:175], v136, s[22:23] offset:16
	global_load_dwordx4 v[168:171], v136, s[22:23]
	s_waitcnt lgkmcnt(1)
	s_waitcnt vmcnt(10)
	v_pk_mul_f32 v[176:177], v[212:213], v[176:177]
	v_pk_mul_f32 v[178:179], v[214:215], v[178:179]
	v_pk_mul_f32 v[180:181], v[216:217], v[180:181]
	v_pk_mul_f32 v[182:183], v[218:219], v[182:183]
	v_pk_mul_f32 v[184:185], v[228:229], v[184:185]
	v_pk_mul_f32 v[186:187], v[230:231], v[186:187]
	v_pk_mul_f32 v[190:191], v[132:133], v[190:191]
	v_pk_mul_f32 v[192:193], v[134:135], v[192:193]
	s_mov_b64 exec, vcc
	v_pk_add_f32 v[212:213], v[176:177], v[184:185]
	v_pk_add_f32 v[214:215], v[178:179], v[186:187]
	v_pk_add_f32 v[216:217], v[180:181], v[190:191]
	v_pk_add_f32 v[218:219], v[182:183], v[192:193]
	s_mov_b64 exec, s[56:57]
	v_pk_add_f32 v[212:213], v[176:177], v[184:185] neg_lo:[0,1] neg_hi:[0,1]
	v_pk_add_f32 v[214:215], v[178:179], v[186:187] neg_lo:[0,1] neg_hi:[0,1]
	v_pk_add_f32 v[216:217], v[180:181], v[190:191] neg_lo:[0,1] neg_hi:[0,1]
	v_pk_add_f32 v[218:219], v[182:183], v[192:193] neg_lo:[0,1] neg_hi:[0,1]
	s_mov_b64 exec, s[100:101]
	v_cvt_pk_bf16_f32 v228, v212, v213
	v_cvt_pk_bf16_f32 v229, v214, v215
	v_cvt_pk_bf16_f32 v230, v216, v217
	v_cvt_pk_bf16_f32 v231, v218, v219
	v_lshl_add_u64 v[132:133], v[142:143], 0, s[26:27]
	global_store_dwordx4 v[132:133], v[228:231], off
	s_waitcnt lgkmcnt(0)
; __device__ __forceinline__ u32x4 pack8(const float (&v)[8]) { u32x4 w; w.x = pk2(v[0], v[1]); w.y = pk2(v[2], v[3]); w.z = pk2(v[4], v[5]); w.w = pk2(v[6], v[7]); return w; }
;     __device__ __forceinline__ bool operator()(Acc& acc, const Unit& u, int wr, int wc, int fr, int fq, const LAS float* rstab) const {
;     ...
;                 if (rope) {
;                     const float sgn = (fq == 0) ? -1.f : 1.f;
; #pragma unroll
;                     for (int ai = 0; ai < 2; ++ai)
; #pragma unroll
;                         for (int m = 0; m < 4; ++m) {
;                             const float rs = rsp[ai * HALF + m * 16] * scale;
;                             const int pos = (rowb + ai * HALF + m * 16) & (SEQ - 1);
;                             const f32x4 c0 = gld<f32x4>(ropec + pos * 8), c1 = gld<f32x4>(ropec + pos * 8 + 4);
;                             const f32x4 s0 = gld<f32x4>(ropes + pos * 8), s1 = gld<f32x4>(ropes + pos * 8 + 4);
;                             float v[8];
; #pragma unroll
;                             for (int e = 0; e < 4; ++e) { v[e] = acc[ai][bj][m][0][e] * rs; v[4 + e] = acc[ai][bj][m][1][e] * rs; }
; #pragma unroll
;                             for (int e = 0; e < 8; ++e) {
;                                 const float p = __shfl_xor(v[e], 16);
;                                 const float cs = e < 4 ? c0[e & 3] : c1[e & 3], sn = e < 4 ? s0[e & 3] : s1[e & 3];
;                                 const float r = v[e] * cs + sgn * p * sn;
;                                 v[e] = (fq < 2) ? r : v[e];
;                             }
;                             gst<u32x4>(p0 + (ai * HALF + m * 16) * pitch, pack8(v));
;                             asm volatile("" ::: "memory");
;                         }
	v_mul_f32_e32 v189, s9, v189
	v_pk_mul_f32 v[212:213], v[84:85], v[188:189] op_sel:[0,1]
	v_pk_mul_f32 v[214:215], v[86:87], v[188:189] op_sel:[0,1]
	v_pk_mul_f32 v[216:217], v[76:77], v[188:189] op_sel:[0,1]
	v_pk_mul_f32 v[218:219], v[78:79], v[188:189] op_sel:[0,1]
	ds_bpermute_b32 v228, v0, v212
	ds_bpermute_b32 v229, v0, v213
	ds_bpermute_b32 v230, v0, v214
	ds_bpermute_b32 v231, v0, v215
	ds_bpermute_b32 v132, v0, v216
	ds_bpermute_b32 v133, v0, v217
	ds_bpermute_b32 v134, v0, v218
	ds_bpermute_b32 v135, v0, v219
	ds_read_b32 v188, v154 offset:640
	v_or_b32_e32 v136, 0x600, v159
	global_load_dwordx4 v[180:183], v136, s[20:21] offset:16
	global_load_dwordx4 v[176:179], v136, s[20:21]
	global_load_dwordx4 v[190:193], v136, s[22:23] offset:16
	global_load_dwordx4 v[184:187], v136, s[22:23]
	s_waitcnt lgkmcnt(1)
	s_waitcnt vmcnt(10)
	v_pk_mul_f32 v[194:195], v[212:213], v[194:195]
	v_pk_mul_f32 v[196:197], v[214:215], v[196:197]
	v_pk_mul_f32 v[200:201], v[216:217], v[200:201]
	v_pk_mul_f32 v[202:203], v[218:219], v[202:203]
	v_pk_mul_f32 v[206:207], v[228:229], v[206:207]
	v_pk_mul_f32 v[208:209], v[230:231], v[208:209]
	v_pk_mul_f32 v[220:221], v[132:133], v[220:221]
	v_pk_mul_f32 v[222:223], v[134:135], v[222:223]
	s_mov_b64 exec, vcc
	v_pk_add_f32 v[212:213], v[194:195], v[206:207]
	v_pk_add_f32 v[214:215], v[196:197], v[208:209]
	v_pk_add_f32 v[216:217], v[200:201], v[220:221]
	v_pk_add_f32 v[218:219], v[202:203], v[222:223]
	s_mov_b64 exec, s[56:57]
	v_pk_add_f32 v[212:213], v[194:195], v[206:207] neg_lo:[0,1] neg_hi:[0,1]
	v_pk_add_f32 v[214:215], v[196:197], v[208:209] neg_lo:[0,1] neg_hi:[0,1]
	v_pk_add_f32 v[216:217], v[200:201], v[220:221] neg_lo:[0,1] neg_hi:[0,1]
	v_pk_add_f32 v[218:219], v[202:203], v[222:223] neg_lo:[0,1] neg_hi:[0,1]
	s_mov_b64 exec, s[100:101]
	v_cvt_pk_bf16_f32 v228, v212, v213
	v_cvt_pk_bf16_f32 v229, v214, v215
	v_cvt_pk_bf16_f32 v230, v216, v217
	v_cvt_pk_bf16_f32 v231, v218, v219
	v_lshl_add_u64 v[132:133], s[16:17], 1, v[142:143]
	global_store_dwordx4 v[132:133], v[228:231], off
	s_waitcnt lgkmcnt(0)
	v_mul_f32_e32 v188, s9, v188
	v_pk_mul_f32 v[212:213], v[52:53], v[188:189] op_sel_hi:[1,0]
	v_pk_mul_f32 v[214:215], v[54:55], v[188:189] op_sel_hi:[1,0]
	v_pk_mul_f32 v[216:217], v[44:45], v[188:189] op_sel_hi:[1,0]
	v_pk_mul_f32 v[218:219], v[46:47], v[188:189] op_sel_hi:[1,0]
	ds_bpermute_b32 v228, v0, v212
	ds_bpermute_b32 v229, v0, v213
	ds_bpermute_b32 v230, v0, v214
	ds_bpermute_b32 v231, v0, v215
	ds_bpermute_b32 v132, v0, v216
	ds_bpermute_b32 v133, v0, v217
	ds_bpermute_b32 v134, v0, v218
	ds_bpermute_b32 v135, v0, v219
	ds_read_b32 v189, v154 offset:704
	s_waitcnt lgkmcnt(1)
	s_waitcnt vmcnt(6)
	v_pk_mul_f32 v[160:161], v[212:213], v[160:161]
	v_pk_mul_f32 v[162:163], v[214:215], v[162:163]
	v_pk_mul_f32 v[164:165], v[216:217], v[164:165]
	v_pk_mul_f32 v[166:167], v[218:219], v[166:167]
	v_pk_mul_f32 v[168:169], v[228:229], v[168:169]
	v_pk_mul_f32 v[170:171], v[230:231], v[170:171]
	v_pk_mul_f32 v[172:173], v[132:133], v[172:173]
	v_pk_mul_f32 v[174:175], v[134:135], v[174:175]
	s_mov_b64 exec, vcc
	v_pk_add_f32 v[212:213], v[160:161], v[168:169]
	v_pk_add_f32 v[214:215], v[162:163], v[170:171]
	v_pk_add_f32 v[216:217], v[164:165], v[172:173]
	v_pk_add_f32 v[218:219], v[166:167], v[174:175]
	s_mov_b64 exec, s[56:57]
	v_pk_add_f32 v[212:213], v[160:161], v[168:169] neg_lo:[0,1] neg_hi:[0,1]
	v_pk_add_f32 v[214:215], v[162:163], v[170:171] neg_lo:[0,1] neg_hi:[0,1]
	v_pk_add_f32 v[216:217], v[164:165], v[172:173] neg_lo:[0,1] neg_hi:[0,1]
	v_pk_add_f32 v[218:219], v[166:167], v[174:175] neg_lo:[0,1] neg_hi:[0,1]
	s_mov_b64 exec, s[100:101]
	v_cvt_pk_bf16_f32 v228, v212, v213
	v_cvt_pk_bf16_f32 v229, v214, v215
	v_cvt_pk_bf16_f32 v230, v216, v217
	v_cvt_pk_bf16_f32 v231, v218, v219
	v_lshl_add_u64 v[132:133], s[14:15], 1, v[142:143]
	global_store_dwordx4 v[132:133], v[228:231], off
	s_waitcnt lgkmcnt(0)
	v_mul_f32_e32 v189, s9, v189
	v_pk_mul_f32 v[212:213], v[24:25], v[188:189] op_sel:[0,1]
	v_pk_mul_f32 v[214:215], v[26:27], v[188:189] op_sel:[0,1]
	v_pk_mul_f32 v[216:217], v[20:21], v[188:189] op_sel:[0,1]
	v_pk_mul_f32 v[218:219], v[22:23], v[188:189] op_sel:[0,1]
	ds_bpermute_b32 v228, v0, v212
	ds_bpermute_b32 v229, v0, v213
	ds_bpermute_b32 v230, v0, v214
	ds_bpermute_b32 v231, v0, v215
	ds_bpermute_b32 v132, v0, v216
	ds_bpermute_b32 v133, v0, v217
	ds_bpermute_b32 v134, v0, v218
	ds_bpermute_b32 v135, v0, v219
	s_waitcnt lgkmcnt(0)
	s_waitcnt vmcnt(2)
	v_pk_mul_f32 v[176:177], v[212:213], v[176:177]
	v_pk_mul_f32 v[178:179], v[214:215], v[178:179]
	v_pk_mul_f32 v[180:181], v[216:217], v[180:181]
	v_pk_mul_f32 v[182:183], v[218:219], v[182:183]
	v_pk_mul_f32 v[184:185], v[228:229], v[184:185]
	v_pk_mul_f32 v[186:187], v[230:231], v[186:187]
	v_pk_mul_f32 v[190:191], v[132:133], v[190:191]
	v_pk_mul_f32 v[192:193], v[134:135], v[192:193]
	s_mov_b64 exec, vcc
	v_pk_add_f32 v[212:213], v[176:177], v[184:185]
	v_pk_add_f32 v[214:215], v[178:179], v[186:187]
	v_pk_add_f32 v[216:217], v[180:181], v[190:191]
	v_pk_add_f32 v[218:219], v[182:183], v[192:193]
	s_mov_b64 exec, s[56:57]
	v_pk_add_f32 v[212:213], v[176:177], v[184:185] neg_lo:[0,1] neg_hi:[0,1]
	v_pk_add_f32 v[214:215], v[178:179], v[186:187] neg_lo:[0,1] neg_hi:[0,1]
	v_pk_add_f32 v[216:217], v[180:181], v[190:191] neg_lo:[0,1] neg_hi:[0,1]
	v_pk_add_f32 v[218:219], v[182:183], v[192:193] neg_lo:[0,1] neg_hi:[0,1]
	s_mov_b64 exec, s[100:101]
	v_cvt_pk_bf16_f32 v228, v212, v213
	v_cvt_pk_bf16_f32 v229, v214, v215
	v_cvt_pk_bf16_f32 v230, v216, v217
	v_cvt_pk_bf16_f32 v231, v218, v219
	v_lshl_add_u64 v[132:133], s[12:13], 1, v[142:143]
	global_store_dwordx4 v[132:133], v[228:231], off
